# conv phase tile loop software-pipelined: next tile's xbc/tap loads issued after this tile's LDS staging, landing during its conv+SiLU compute and stores; on top of v41
# baseline (speedup 1.0000x reference)
; __device__ __forceinline__ void conv_phase(CParams& p, int layer, float* smf) {
;     ...
;     const int nCt = 3072 / 64, nRt = MT / 64;
;     for (int t = blockIdx.x; t < nCt * nRt; t += gridDim.x) {
;         const int rt = t / nCt, ct = t - rt * nCt;
;         const int r0 = rt * 64, c0 = ct * 64;
;         const bool first = r0 < ML ? ((r0 & (SEQ - 1)) == 0) : (((r0 - ML) & (CTX - 1)) == 0);
;         const bool last = r0 < ML ? (((r0 + 64) & (SEQ - 1)) == 0) : ((((r0 + 64) - ML) & (CTX - 1)) == 0);
;         lds_sync();
;         for (int e = tid; e < 66 * 8; e += 256) {
;             const int rr = e >> 3, c8 = (e & 7) * 8;
;             const int row = r0 - 1 + rr;
;             u32x4 v = (u32x4){0u, 0u, 0u, 0u};
;             if (!((rr == 0 && first) || (rr == 65 && last))) v = *(const u32x4*)(xbc + (size_t)row * 3072 + c0 + c8);
;             float* d = sin_ + rr * 65 + c8;
;             d[0] = __uint_as_float(v.x << 16); d[1] = __uint_as_float(v.x & 0xffff0000u);
;             d[2] = __uint_as_float(v.y << 16); d[3] = __uint_as_float(v.y & 0xffff0000u);
;             d[4] = __uint_as_float(v.z << 16); d[5] = __uint_as_float(v.z & 0xffff0000u);
;             d[6] = __uint_as_float(v.w << 16); d[7] = __uint_as_float(v.w & 0xffff0000u);
;         }
;         lds_sync();
;         {
;             const int c = tid & 63;
;             const float w0 = cw[c0 + c], w1 = cw[3072 + c0 + c], w2 = cw[2 * 3072 + c0 + c], bb = cb[c0 + c];
.LBB0_402:
	s_mov_b32 s2, s1
	v_readlane_b32 s8, v248, 24
	s_mov_b32 s1, s2
	s_cmp_lg_u32 s2, 8
	v_readlane_b32 s9, v248, 25
	s_cbranch_scc1 .LBB0_422
	v_readlane_b32 s4, v250, 18
	v_readlane_b32 s5, v250, 19
	s_waitcnt vmcnt(29)
	v_mov_b32_e32 v9, v167
	s_andn2_b64 vcc, exec, s[4:5]
	s_cbranch_vccnz .LBB0_422
	s_load_dwordx2 s[4:5], s[8:9], 0xd0
	s_load_dwordx4 s[12:15], s[8:9], 0x90
	s_lshr_b32 s6, s75, 1
	s_waitcnt vmcnt(27)
	v_lshlrev_b32_e32 v0, 4, v9
	s_mul_i32 s8, s6, 0x9000
	s_waitcnt lgkmcnt(0)
	s_add_u32 s46, s4, 0x2700000
	s_addc_u32 s47, s5, 0
	s_mul_i32 s16, s6, 0x3000
	s_add_u32 s6, s4, 0xed00000
	v_and_b32_e32 v8, 48, v0
	s_addc_u32 s7, s5, 0
	v_ashrrev_i32_e32 v19, 2, v9
	v_mul_u32_u24_e32 v0, 0x104, v8
	v_and_b32_e32 v1, -4, v9
	s_add_u32 s8, s12, s8
	s_waitcnt vmcnt(20)
	v_add3_u32 v20, 0, v0, v1
	v_and_b32_e32 v0, 15, v19
	v_lshlrev_b32_e32 v1, 5, v9
	s_addc_u32 s9, s13, 0
	v_and_or_b32 v0, v1, 32, v0
	s_add_u32 s12, s14, s16
	v_lshlrev_b32_e32 v164, 4, v0
	s_addc_u32 s13, s15, 0
	v_and_b32_e32 v16, 63, v9
	v_lshl_add_u64 v[0:1], s[4:5], 0, v[164:165]
	s_mov_b64 s[14:15], 0x13f80000
	v_ashrrev_i32_e32 v2, 6, v9
	v_lshlrev_b32_e32 v3, 2, v16
	v_lshl_add_u64 v[10:11], v[0:1], 0, s[14:15]
	s_mov_b64 s[14:15], 0x15000000
	v_add_u32_e32 v4, 0, v3
	s_waitcnt vmcnt(19)
	v_lshl_add_u64 v[12:13], v[0:1], 0, s[14:15]
	v_mul_lo_u32 v0, v2, s94
	s_movk_i32 s2, 0x210
	v_lshlrev_b32_e32 v5, 8, v16
	v_mul_lo_u32 v6, v19, s94
	v_lshlrev_b32_e32 v7, 2, v8
	v_add_u32_e32 v24, v4, v0
	v_add3_u32 v25, 0, v0, v3
	v_lshlrev_b32_e32 v0, 2, v2
	v_cmp_gt_i32_e64 s[42:43], s2, v9
	v_or_b32_e32 v17, 0xc00, v16
	v_or_b32_e32 v18, 0x1800, v16
	v_or_b32_e32 v21, 0xfffff600, v8
	v_add3_u32 v22, 0, v6, v7
	v_add_u32_e32 v23, 0xfffff800, v19
	v_add3_u32 v26, v4, v5, v0
	v_add_u32_e32 v27, 0x410, v25
	v_add_u32_e32 v28, 0x820, v25
	v_add_u32_e32 v29, 0xc30, v25
	v_add_u32_e32 v30, 0x1040, v25
	v_add_u32_e32 v31, 0x1450, v25
	s_waitcnt vmcnt(15)
	v_add_u32_e32 v32, 0x1860, v25
	v_add_u32_e32 v33, 0x1c70, v25
	v_add_u32_e32 v34, 0x2080, v25
	v_add_u32_e32 v35, 0x2490, v25
	s_waitcnt vmcnt(11)
	v_add_u32_e32 v36, 0x28a0, v25
	v_add_u32_e32 v37, 0x2cb0, v25
	v_add_u32_e32 v38, 0x30c0, v25
	v_add_u32_e32 v39, 0x34d0, v25
	s_waitcnt vmcnt(4)
	v_add_u32_e32 v40, 0x38e0, v25
	v_add_u32_e32 v41, 0x3cf0, v25
	v_lshlrev_b32_e32 v42, 3, v9
	s_mov_b32 s48, s38
	s_mov_b32 s100, s48
	s_mul_hi_i32 s101, s100, 0x2aaaaaab
	s_lshr_b32 s20, s101, 31
	s_ashr_i32 s101, s101, 3
	s_add_i32 s101, s101, s20
	s_mul_i32 s21, s101, 0xffffffd0
	s_add_i32 s21, s21, s100
	s_lshl_b32 s49, s101, 6
	s_lshl_b32 s24, s21, 6
	s_cmpk_lt_i32 s100, 0x3000
	s_cselect_b32 s20, 0x7f, 3
	s_movk_i32 s21, 0x1fc0
	s_cselect_b32 s22, s21, 0xc0
	s_and_b32 s20, s20, s101
	s_cmp_eq_u32 s20, 0
	s_cselect_b64 s[44:45], -1, 0
	s_add_i32 s20, s49, 64
	s_and_b32 s20, s20, s22
	s_cmp_eq_u32 s20, 0
	s_cselect_b64 s[22:23], -1, 0
	s_mov_b32 s101, s24
	s_ashr_i32 s25, s24, 31
	s_lshl_b64 s[24:25], s[24:25], 1
	s_add_u32 s24, s46, s24
	s_addc_u32 s25, s47, s25
	s_add_i32 s49, s49, -1
	s_mov_b64 s[26:27], exec
	v_and_b32_e32 v87, 56, v42
	v_ashrrev_i32_e32 v86, 3, v9
	v_lshlrev_b32_e32 v88, 1, v87
	v_mov_b32_e32 v89, 0
	v_add_u32_e32 v90, s49, v86
	v_mov_b64_e32 v[82:83], s[24:25]
	s_movk_i32 s2, 0x1800
	v_mad_i64_i32 v[82:83], s[50:51], v90, s2, v[82:83]
	v_lshl_add_u64 v[82:83], v[82:83], 0, v[88:89]
	v_mov_b32_e32 v48, 0
	v_mov_b32_e32 v49, 0
	v_mov_b32_e32 v50, 0
	v_mov_b32_e32 v51, 0
	v_mov_b32_e32 v56, 0
	v_mov_b32_e32 v57, 0
	v_mov_b32_e32 v58, 0
	v_mov_b32_e32 v59, 0
	s_mov_b64 s[50:51], 0x60000
	v_lshl_add_u64 v[84:85], v[82:83], 0, s[50:51]
	v_cmp_gt_u32_e64 s[50:51], 8, v9
	v_cmp_gt_u32_e32 vcc, 16, v9
	s_nop 1
	s_andn2_b64 s[20:21], vcc, s[22:23]
	s_or_b64 s[50:51], s[50:51], s[20:21]
	s_and_b64 exec, s[26:27], s[50:51]
	global_load_dwordx4 v[56:59], v[84:85], off
	s_mov_b64 exec, s[26:27]
	v_cmp_gt_u32_e32 vcc, 8, v9
	s_nop 1
	s_and_b64 s[50:51], s[44:45], vcc
	s_andn2_b64 exec, s[26:27], s[50:51]
	global_load_dwordx4 v[48:51], v[82:83], off
	s_mov_b64 exec, s[26:27]
	s_mov_b64 s[50:51], 0x30000
	v_lshl_add_u64 v[84:85], v[82:83], 0, s[50:51]
	global_load_dwordx4 v[52:55], v[84:85], off
	v_or_b32_e32 v60, s101, v16
	v_ashrrev_i32_e32 v61, 31, v60
	v_add_u32_e32 v62, s101, v17
	v_lshlrev_b64 v[64:65], 2, v[60:61]
	v_ashrrev_i32_e32 v63, 31, v62
	v_lshl_add_u64 v[60:61], s[8:9], 0, v[64:65]
	v_lshl_add_u64 v[62:63], v[62:63], 2, s[8:9]
	global_load_dword v66, v[60:61], off
	v_lshl_add_u64 v[64:65], s[12:13], 0, v[64:65]
	global_load_dword v67, v[62:63], off
	v_add_u32_e32 v62, s101, v18
	v_ashrrev_i32_e32 v63, 31, v62
	v_lshl_add_u64 v[62:63], v[62:63], 2, s[8:9]
	global_load_dword v68, v[62:63], off
	global_load_dword v69, v[64:65], off
	s_branch .LBB0_406

; __device__ __forceinline__ void conv_phase(CParams& p, int layer, float* smf) {
;     ...
;     const int nCt = 3072 / 64, nRt = MT / 64;
;     for (int t = blockIdx.x; t < nCt * nRt; t += gridDim.x) {
;         const int rt = t / nCt, ct = t - rt * nCt;
;         const int r0 = rt * 64, c0 = ct * 64;
;         const bool first = r0 < ML ? ((r0 & (SEQ - 1)) == 0) : (((r0 - ML) & (CTX - 1)) == 0);
;         const bool last = r0 < ML ? (((r0 + 64) & (SEQ - 1)) == 0) : ((((r0 + 64) - ML) & (CTX - 1)) == 0);
;         lds_sync();
;         for (int e = tid; e < 66 * 8; e += 256) {
;             const int rr = e >> 3, c8 = (e & 7) * 8;
;             const int row = r0 - 1 + rr;
;             u32x4 v = (u32x4){0u, 0u, 0u, 0u};
;             if (!((rr == 0 && first) || (rr == 65 && last))) v = *(const u32x4*)(xbc + (size_t)row * 3072 + c0 + c8);
;             float* d = sin_ + rr * 65 + c8;
;             d[0] = __uint_as_float(v.x << 16); d[1] = __uint_as_float(v.x & 0xffff0000u);
;             d[2] = __uint_as_float(v.y << 16); d[3] = __uint_as_float(v.y & 0xffff0000u);
;             d[4] = __uint_as_float(v.z << 16); d[5] = __uint_as_float(v.z & 0xffff0000u);
;             d[6] = __uint_as_float(v.w << 16); d[7] = __uint_as_float(v.w & 0xffff0000u);
;         }
;         lds_sync();
;         {
;             const int c = tid & 63;
;             const float w0 = cw[c0 + c], w1 = cw[3072 + c0 + c], w2 = cw[2 * 3072 + c0 + c], bb = cb[c0 + c];
.LBB0_406:
	s_mul_hi_i32 s14, s48, 0x2aaaaaab
	s_lshr_b32 s15, s14, 31
	s_ashr_i32 s17, s14, 3
	s_add_i32 s17, s17, s15
	s_mul_i32 s15, s17, 0xffffffd0
	s_add_i32 s15, s15, s48
	s_lshl_b32 s14, s17, 6
	s_lshl_b32 s16, s15, 6
	s_waitcnt vmcnt(63) expcnt(7) lgkmcnt(15)
	s_barrier
	s_and_saveexec_b64 s[18:19], s[42:43]
	s_cbranch_execz .LBB0_411
	s_mov_b64 s[26:27], exec
	v_and_b32_e32 v7, 56, v42
	v_ashrrev_i32_e32 v6, 3, v9
	v_mul_lo_u32 v70, v6, s94
	v_lshlrev_b32_e32 v71, 2, v7
	v_add3_u32 v70, 0, v70, v71
	v_add_u32_e32 v71, 0x2080, v70
	v_add_u32_e32 v72, 0x4100, v70
	s_waitcnt vmcnt(5)
	v_lshlrev_b32_e32 v73, 16, v48
	v_and_b32_e32 v74, 0xffff0000, v48
	ds_write2_b32 v70, v73, v74 offset1:1
	v_lshlrev_b32_e32 v75, 16, v49
	v_and_b32_e32 v76, 0xffff0000, v49
	ds_write2_b32 v70, v75, v76 offset0:2 offset1:3
	v_lshlrev_b32_e32 v73, 16, v50
	v_and_b32_e32 v74, 0xffff0000, v50
	ds_write2_b32 v70, v73, v74 offset0:4 offset1:5
	v_lshlrev_b32_e32 v75, 16, v51
	v_and_b32_e32 v76, 0xffff0000, v51
	ds_write2_b32 v70, v75, v76 offset0:6 offset1:7
	s_waitcnt vmcnt(4)
	v_lshlrev_b32_e32 v73, 16, v52
	v_and_b32_e32 v74, 0xffff0000, v52
	ds_write2_b32 v71, v73, v74 offset1:1
	v_lshlrev_b32_e32 v75, 16, v53
	v_and_b32_e32 v76, 0xffff0000, v53
	ds_write2_b32 v71, v75, v76 offset0:2 offset1:3
	v_lshlrev_b32_e32 v73, 16, v54
	v_and_b32_e32 v74, 0xffff0000, v54
	ds_write2_b32 v71, v73, v74 offset0:4 offset1:5
	v_lshlrev_b32_e32 v75, 16, v55
	v_and_b32_e32 v76, 0xffff0000, v55
	ds_write2_b32 v71, v75, v76 offset0:6 offset1:7
	v_cmp_gt_u32_e32 vcc, 16, v9
	s_nop 1
	s_and_b64 exec, s[26:27], vcc
	v_lshlrev_b32_e32 v73, 16, v56
	v_and_b32_e32 v74, 0xffff0000, v56
	ds_write2_b32 v72, v73, v74 offset1:1
	v_lshlrev_b32_e32 v75, 16, v57
	v_and_b32_e32 v76, 0xffff0000, v57
	ds_write2_b32 v72, v75, v76 offset0:2 offset1:3
	v_lshlrev_b32_e32 v73, 16, v58
	v_and_b32_e32 v74, 0xffff0000, v58
	ds_write2_b32 v72, v73, v74 offset0:4 offset1:5
	v_lshlrev_b32_e32 v75, 16, v59
	v_and_b32_e32 v76, 0xffff0000, v59
	ds_write2_b32 v72, v75, v76 offset0:6 offset1:7
	s_mov_b64 exec, s[26:27]
.LBB0_411:
	s_or_b64 exec, exec, s[18:19]
	v_or_b32_e32 v0, s16, v16
	v_ashrrev_i32_e32 v1, 31, v0
	v_add_u32_e32 v2, s16, v17
	v_lshlrev_b64 v[4:5], 2, v[0:1]
	v_ashrrev_i32_e32 v3, 31, v2
	v_lshl_add_u64 v[0:1], s[8:9], 0, v[4:5]
	v_lshl_add_u64 v[2:3], v[2:3], 2, s[8:9]
	s_waitcnt lgkmcnt(0)
	s_barrier
	s_waitcnt vmcnt(0)
	v_mov_b32_e32 v0, v66
	v_mov_b32_e32 v1, v67
	v_mov_b32_e32 v2, v68
	v_mov_b32_e32 v3, v69
	s_add_i32 s100, s48, s74
	s_cmpk_lt_i32 s100, 0x3180
	s_cbranch_scc0 .Lconv_nopf
	s_mul_hi_i32 s101, s100, 0x2aaaaaab
	s_lshr_b32 s20, s101, 31
	s_ashr_i32 s101, s101, 3
	s_add_i32 s101, s101, s20
	s_mul_i32 s21, s101, 0xffffffd0
	s_add_i32 s21, s21, s100
	s_lshl_b32 s49, s101, 6
	s_lshl_b32 s24, s21, 6
	s_cmpk_lt_i32 s100, 0x3000
	s_cselect_b32 s20, 0x7f, 3
	s_movk_i32 s21, 0x1fc0
	s_cselect_b32 s22, s21, 0xc0
	s_and_b32 s20, s20, s101
	s_cmp_eq_u32 s20, 0
	s_cselect_b64 s[44:45], -1, 0
	s_add_i32 s20, s49, 64
	s_and_b32 s20, s20, s22
	s_cmp_eq_u32 s20, 0
	s_cselect_b64 s[22:23], -1, 0
	s_mov_b32 s101, s24
	s_ashr_i32 s25, s24, 31
	s_lshl_b64 s[24:25], s[24:25], 1
	s_add_u32 s24, s46, s24
	s_addc_u32 s25, s47, s25
	s_add_i32 s49, s49, -1
	s_mov_b64 s[26:27], exec
	v_and_b32_e32 v87, 56, v42
	v_ashrrev_i32_e32 v86, 3, v9
	v_lshlrev_b32_e32 v88, 1, v87
	v_mov_b32_e32 v89, 0
	v_add_u32_e32 v90, s49, v86
	v_mov_b64_e32 v[82:83], s[24:25]
	s_movk_i32 s2, 0x1800
	v_mad_i64_i32 v[82:83], s[50:51], v90, s2, v[82:83]
	v_lshl_add_u64 v[82:83], v[82:83], 0, v[88:89]
	v_mov_b32_e32 v48, 0
	v_mov_b32_e32 v49, 0
	v_mov_b32_e32 v50, 0
	v_mov_b32_e32 v51, 0
	v_mov_b32_e32 v56, 0
	v_mov_b32_e32 v57, 0
	v_mov_b32_e32 v58, 0
	v_mov_b32_e32 v59, 0
	s_mov_b64 s[50:51], 0x60000
	v_lshl_add_u64 v[84:85], v[82:83], 0, s[50:51]
	v_cmp_gt_u32_e64 s[50:51], 8, v9
	v_cmp_gt_u32_e32 vcc, 16, v9
	s_nop 1
	s_andn2_b64 s[20:21], vcc, s[22:23]
	s_or_b64 s[50:51], s[50:51], s[20:21]
	s_and_b64 exec, s[26:27], s[50:51]
	global_load_dwordx4 v[56:59], v[84:85], off
	s_mov_b64 exec, s[26:27]
	v_cmp_gt_u32_e32 vcc, 8, v9
	s_nop 1
	s_and_b64 s[50:51], s[44:45], vcc
	s_andn2_b64 exec, s[26:27], s[50:51]
	global_load_dwordx4 v[48:51], v[82:83], off
	s_mov_b64 exec, s[26:27]
	s_mov_b64 s[50:51], 0x30000
	v_lshl_add_u64 v[84:85], v[82:83], 0, s[50:51]
	global_load_dwordx4 v[52:55], v[84:85], off
	v_or_b32_e32 v60, s101, v16
	v_ashrrev_i32_e32 v61, 31, v60
	v_add_u32_e32 v62, s101, v17
	v_lshlrev_b64 v[64:65], 2, v[60:61]
	v_ashrrev_i32_e32 v63, 31, v62
	v_lshl_add_u64 v[60:61], s[8:9], 0, v[64:65]
	v_lshl_add_u64 v[62:63], v[62:63], 2, s[8:9]
	global_load_dword v66, v[60:61], off
	v_lshl_add_u64 v[64:65], s[12:13], 0, v[64:65]
	global_load_dword v67, v[62:63], off
	v_add_u32_e32 v62, s101, v18
	v_ashrrev_i32_e32 v63, 31, v62
	v_lshl_add_u64 v[62:63], v[62:63], 2, s[8:9]
	global_load_dword v68, v[62:63], off
	global_load_dword v69, v[64:65], off
; __device__ __forceinline__ float siluf(float v) { return v / (1.f + __expf(-v)); }
; __device__ __forceinline__ void conv_phase(CParams& p, int layer, float* smf) {
;     ...
;         {
;             const int c = tid & 63;
;             const float w0 = cw[c0 + c], w1 = cw[3072 + c0 + c], w2 = cw[2 * 3072 + c0 + c], bb = cb[c0 + c];
; #pragma unroll
;             for (int k = 0; k < 16; ++k) {
;                 const int tt = (tid >> 6) + k * 4;
;                 const float v = w0 * sin_[tt * 65 + c] + w1 * sin_[(tt + 1) * 65 + c] + w2 * sin_[(tt + 2) * 65 + c] + bb;
;                 sout[c * 65 + tt] = siluf(v);
;             }
;         }
.Lconv_nopf:
	s_cmp_gt_i32 s15, 31
	ds_read_b32 v6, v24
	ds_read2_b32 v[4:5], v25 offset0:65 offset1:130
	s_movk_i32 s50, 0xb00
	s_movk_i32 s51, 0x1600
	s_waitcnt vmcnt(2) lgkmcnt(0)
	v_mul_f32_e32 v4, v1, v4
	v_fmac_f32_e32 v4, v0, v6
	s_waitcnt vmcnt(1)
	v_fmac_f32_e32 v4, v2, v5
	s_waitcnt vmcnt(0)
	v_add_f32_e32 v4, v3, v4
	v_mul_f32_e32 v5, 0xbfb8aa3b, v4
	v_exp_f32_e32 v5, v5
	s_nop 0
	v_add_f32_e32 v5, 1.0, v5
	v_div_scale_f32 v6, s[18:19], v5, v5, v4
	v_rcp_f32_e32 v7, v6
	s_nop 0
	v_fma_f32 v14, -v6, v7, 1.0
	v_fmac_f32_e32 v7, v14, v7
	v_div_scale_f32 v14, vcc, v4, v5, v4
	v_mul_f32_e32 v15, v14, v7
	v_fma_f32 v43, -v6, v15, v14
	v_fmac_f32_e32 v15, v43, v7
	v_fma_f32 v6, -v6, v15, v14
	v_div_fmas_f32 v6, v6, v7, v15
	v_div_fixup_f32 v6, v6, v5, v4
	ds_read_b32 v7, v25 offset:1040
	ds_read2_b32 v[4:5], v27 offset0:65 offset1:130
	s_waitcnt lgkmcnt(0)
	v_mul_f32_e32 v4, v1, v4
	v_fmac_f32_e32 v4, v0, v7
	v_fmac_f32_e32 v4, v2, v5
	v_add_f32_e32 v4, v3, v4
	v_mul_f32_e32 v5, 0xbfb8aa3b, v4
	v_exp_f32_e32 v5, v5
	s_nop 0
	v_add_f32_e32 v5, 1.0, v5
	v_div_scale_f32 v7, s[18:19], v5, v5, v4
	v_rcp_f32_e32 v14, v7
	s_nop 0
	v_fma_f32 v15, -v7, v14, 1.0
	v_fmac_f32_e32 v14, v15, v14
	v_div_scale_f32 v15, vcc, v4, v5, v4
	v_mul_f32_e32 v43, v15, v14
	v_fma_f32 v44, -v7, v43, v15
	v_fmac_f32_e32 v43, v44, v14
	v_fma_f32 v7, -v7, v43, v15
	v_div_fmas_f32 v7, v7, v14, v43
	v_div_fixup_f32 v5, v7, v5, v4
	v_add_u32_e32 v4, 0x4000, v26
	ds_write2_b32 v4, v6, v5 offset0:194 offset1:198
	ds_read_b32 v5, v27 offset:1040
	ds_read2_b32 v[6:7], v28 offset0:65 offset1:130
	s_waitcnt lgkmcnt(0)
	v_mul_f32_e32 v6, v1, v6
	v_fmac_f32_e32 v6, v0, v5
	v_fmac_f32_e32 v6, v2, v7
	v_add_f32_e32 v5, v3, v6
	v_mul_f32_e32 v6, 0xbfb8aa3b, v5
	v_exp_f32_e32 v6, v6
	s_nop 0
	v_add_f32_e32 v6, 1.0, v6
	v_div_scale_f32 v7, s[18:19], v6, v6, v5
	v_rcp_f32_e32 v14, v7
	s_nop 0
	v_fma_f32 v15, -v7, v14, 1.0
	v_fmac_f32_e32 v14, v15, v14
	v_div_scale_f32 v15, vcc, v5, v6, v5
	v_mul_f32_e32 v43, v15, v14
	v_fma_f32 v44, -v7, v43, v15
	v_fmac_f32_e32 v43, v44, v14
	v_fma_f32 v7, -v7, v43, v15
	v_div_fmas_f32 v7, v7, v14, v43
	v_div_fixup_f32 v5, v7, v6, v5
	ds_read_b32 v14, v28 offset:1040
	ds_read2_b32 v[6:7], v29 offset0:65 offset1:130
	s_waitcnt lgkmcnt(0)
	v_mul_f32_e32 v6, v1, v6
	v_fmac_f32_e32 v6, v0, v14
	v_fmac_f32_e32 v6, v2, v7
	v_add_f32_e32 v6, v3, v6
	v_mul_f32_e32 v7, 0xbfb8aa3b, v6
	v_exp_f32_e32 v7, v7
	s_nop 0
	v_add_f32_e32 v7, 1.0, v7
	v_div_scale_f32 v14, s[18:19], v7, v7, v6
	v_rcp_f32_e32 v15, v14
	s_nop 0
	v_fma_f32 v43, -v14, v15, 1.0
	v_fmac_f32_e32 v15, v43, v15
	v_div_scale_f32 v43, vcc, v6, v7, v6
	v_mul_f32_e32 v44, v43, v15
	v_fma_f32 v45, -v14, v44, v43
	v_fmac_f32_e32 v44, v45, v15
	v_fma_f32 v14, -v14, v44, v43
	v_div_fmas_f32 v14, v14, v15, v44
	v_div_fixup_f32 v6, v14, v7, v6
	ds_write2_b32 v4, v5, v6 offset0:202 offset1:206
	ds_read_b32 v5, v29 offset:1040
	ds_read2_b32 v[6:7], v30 offset0:65 offset1:130
	s_waitcnt lgkmcnt(0)
	v_mul_f32_e32 v6, v1, v6
	v_fmac_f32_e32 v6, v0, v5
	v_fmac_f32_e32 v6, v2, v7
	v_add_f32_e32 v5, v3, v6
	v_mul_f32_e32 v6, 0xbfb8aa3b, v5
	v_exp_f32_e32 v6, v6
	s_nop 0
	v_add_f32_e32 v6, 1.0, v6
	v_div_scale_f32 v7, s[18:19], v6, v6, v5
	v_rcp_f32_e32 v14, v7
	s_nop 0
	v_fma_f32 v15, -v7, v14, 1.0
	v_fmac_f32_e32 v14, v15, v14
	v_div_scale_f32 v15, vcc, v5, v6, v5
	v_mul_f32_e32 v43, v15, v14
	v_fma_f32 v44, -v7, v43, v15
	v_fmac_f32_e32 v43, v44, v14
	v_fma_f32 v7, -v7, v43, v15
	v_div_fmas_f32 v7, v7, v14, v43
	v_div_fixup_f32 v5, v7, v6, v5
	ds_read_b32 v14, v30 offset:1040
	ds_read2_b32 v[6:7], v31 offset0:65 offset1:130
	s_waitcnt lgkmcnt(0)
	v_mul_f32_e32 v6, v1, v6
	v_fmac_f32_e32 v6, v0, v14
	v_fmac_f32_e32 v6, v2, v7
	v_add_f32_e32 v6, v3, v6
	v_mul_f32_e32 v7, 0xbfb8aa3b, v6
	v_exp_f32_e32 v7, v7
	s_nop 0
	v_add_f32_e32 v7, 1.0, v7
	v_div_scale_f32 v14, s[18:19], v7, v7, v6
	v_rcp_f32_e32 v15, v14
	s_nop 0
	v_fma_f32 v43, -v14, v15, 1.0
	v_fmac_f32_e32 v15, v43, v15
	v_div_scale_f32 v43, vcc, v6, v7, v6
	v_mul_f32_e32 v44, v43, v15
	v_fma_f32 v45, -v14, v44, v43
	v_fmac_f32_e32 v44, v45, v15
	v_fma_f32 v14, -v14, v44, v43
	v_div_fmas_f32 v14, v14, v15, v44
	v_div_fixup_f32 v6, v14, v7, v6
	ds_write2_b32 v4, v5, v6 offset0:210 offset1:214
	ds_read_b32 v5, v31 offset:1040
	ds_read2_b32 v[6:7], v32 offset0:65 offset1:130
	s_waitcnt lgkmcnt(0)
	v_mul_f32_e32 v6, v1, v6
	v_fmac_f32_e32 v6, v0, v5
	v_fmac_f32_e32 v6, v2, v7
	v_add_f32_e32 v5, v3, v6
	v_mul_f32_e32 v6, 0xbfb8aa3b, v5
	v_exp_f32_e32 v6, v6
	s_nop 0
	v_add_f32_e32 v6, 1.0, v6
	v_div_scale_f32 v7, s[18:19], v6, v6, v5
	v_rcp_f32_e32 v14, v7
	s_nop 0
	v_fma_f32 v15, -v7, v14, 1.0
	v_fmac_f32_e32 v14, v15, v14
	v_div_scale_f32 v15, vcc, v5, v6, v5
	v_mul_f32_e32 v43, v15, v14
	v_fma_f32 v44, -v7, v43, v15
	v_fmac_f32_e32 v43, v44, v14
	v_fma_f32 v7, -v7, v43, v15
	v_div_fmas_f32 v7, v7, v14, v43
	v_div_fixup_f32 v5, v7, v6, v5
	ds_read_b32 v14, v32 offset:1040
	ds_read2_b32 v[6:7], v33 offset0:65 offset1:130
	s_waitcnt lgkmcnt(0)
	v_mul_f32_e32 v6, v1, v6
	v_fmac_f32_e32 v6, v0, v14
	v_fmac_f32_e32 v6, v2, v7
	v_add_f32_e32 v6, v3, v6
	v_mul_f32_e32 v7, 0xbfb8aa3b, v6
	v_exp_f32_e32 v7, v7
	s_nop 0
	v_add_f32_e32 v7, 1.0, v7
	v_div_scale_f32 v14, s[18:19], v7, v7, v6
	v_rcp_f32_e32 v15, v14
	s_nop 0
	v_fma_f32 v43, -v14, v15, 1.0
	v_fmac_f32_e32 v15, v43, v15
	v_div_scale_f32 v43, vcc, v6, v7, v6
	v_mul_f32_e32 v44, v43, v15
	v_fma_f32 v45, -v14, v44, v43
	v_fmac_f32_e32 v44, v45, v15
	v_fma_f32 v14, -v14, v44, v43
	v_div_fmas_f32 v14, v14, v15, v44
	v_div_fixup_f32 v6, v14, v7, v6
	ds_write2_b32 v4, v5, v6 offset0:218 offset1:222
	ds_read_b32 v6, v33 offset:1040
	ds_read2_b32 v[4:5], v34 offset0:65 offset1:130
	s_waitcnt lgkmcnt(0)
; __device__ __forceinline__ unsigned pack2(float a, float b) { const f32v2_t v = {a, b}; return __builtin_bit_cast(unsigned, __builtin_convertvector(v, bf16v2_t)); }
; __device__ __forceinline__ float siluf(float v) { return v / (1.f + __expf(-v)); }
; __device__ __forceinline__ void conv_phase(CParams& p, int layer, float* smf) {
;     ...
; #pragma unroll
;             for (int k = 0; k < 16; ++k) {
;                 const int tt = (tid >> 6) + k * 4;
;                 const float v = w0 * sin_[tt * 65 + c] + w1 * sin_[(tt + 1) * 65 + c] + w2 * sin_[(tt + 2) * 65 + c] + bb;
;                 sout[c * 65 + tt] = siluf(v);
;             }
;         }
;         lds_sync();
;         const int q = tid >> 2, e16 = (tid & 3) * 16;
;         if (c0 >= 2048) {
;             u32x4 o0, o1;
;             o0.x = pack2(sout[(e16 + 0) * 65 + q], sout[(e16 + 1) * 65 + q]); o0.y = pack2(sout[(e16 + 2) * 65 + q], sout[(e16 + 3) * 65 + q]);
;             o0.z = pack2(sout[(e16 + 4) * 65 + q], sout[(e16 + 5) * 65 + q]); o0.w = pack2(sout[(e16 + 6) * 65 + q], sout[(e16 + 7) * 65 + q]);
;             o1.x = pack2(sout[(e16 + 8) * 65 + q], sout[(e16 + 9) * 65 + q]); o1.y = pack2(sout[(e16 + 10) * 65 + q], sout[(e16 + 11) * 65 + q]);
;             o1.z = pack2(sout[(e16 + 12) * 65 + q], sout[(e16 + 13) * 65 + q]); o1.w = pack2(sout[(e16 + 14) * 65 + q], sout[(e16 + 15) * 65 + q]);
;             if (c0 < 2560) {
;                 bf16_t* dst = Bn + (c0 - 2048) + (size_t)(r0 + q) * 512 + e16;
;                 *(u32x4*)dst = o0; *(u32x4*)(dst + 8) = o1;
;             } else {
;                 *(u32x4*)(Cn + frag_off(r0 + q, c0 - 2560 + e16, 512)) = o0;
;                 *(u32x4*)(Cn + frag_off(r0 + q, c0 - 2560 + e16 + 8, 512)) = o1;
;             }
	v_mul_f32_e32 v4, v1, v4
	v_fmac_f32_e32 v4, v0, v6
	v_fmac_f32_e32 v4, v2, v5
	v_add_f32_e32 v4, v3, v4
	v_mul_f32_e32 v5, 0xbfb8aa3b, v4
	v_exp_f32_e32 v5, v5
	s_nop 0
	v_add_f32_e32 v5, 1.0, v5
	v_div_scale_f32 v6, s[18:19], v5, v5, v4
	v_rcp_f32_e32 v7, v6
	s_nop 0
	v_fma_f32 v14, -v6, v7, 1.0
	v_fmac_f32_e32 v7, v14, v7
	v_div_scale_f32 v14, vcc, v4, v5, v4
	v_mul_f32_e32 v15, v14, v7
	v_fma_f32 v43, -v6, v15, v14
	v_fmac_f32_e32 v15, v43, v7
	v_fma_f32 v6, -v6, v15, v14
	v_div_fmas_f32 v6, v6, v7, v15
	v_div_fixup_f32 v4, v6, v5, v4
	ds_write_b32 v26, v4 offset:17288
	ds_read_b32 v6, v34 offset:1040
	ds_read2_b32 v[4:5], v35 offset0:65 offset1:130
	s_waitcnt lgkmcnt(0)
	v_mul_f32_e32 v4, v1, v4
	v_fmac_f32_e32 v4, v0, v6
	v_fmac_f32_e32 v4, v2, v5
	v_add_f32_e32 v4, v3, v4
	v_mul_f32_e32 v5, 0xbfb8aa3b, v4
	v_exp_f32_e32 v5, v5
	s_nop 0
	v_add_f32_e32 v5, 1.0, v5
	v_div_scale_f32 v6, s[18:19], v5, v5, v4
	v_rcp_f32_e32 v7, v6
	s_nop 0
	v_fma_f32 v14, -v6, v7, 1.0
	v_fmac_f32_e32 v7, v14, v7
	v_div_scale_f32 v14, vcc, v4, v5, v4
	v_mul_f32_e32 v15, v14, v7
	v_fma_f32 v43, -v6, v15, v14
	v_fmac_f32_e32 v15, v43, v7
	v_fma_f32 v6, -v6, v15, v14
	v_div_fmas_f32 v6, v6, v7, v15
	v_div_fixup_f32 v4, v6, v5, v4
	ds_write_b32 v26, v4 offset:17304
	ds_read_b32 v6, v35 offset:1040
	ds_read2_b32 v[4:5], v36 offset0:65 offset1:130
	s_waitcnt lgkmcnt(0)
	v_mul_f32_e32 v4, v1, v4
	v_fmac_f32_e32 v4, v0, v6
	v_fmac_f32_e32 v4, v2, v5
	v_add_f32_e32 v4, v3, v4
	v_mul_f32_e32 v5, 0xbfb8aa3b, v4
	v_exp_f32_e32 v5, v5
	s_nop 0
	v_add_f32_e32 v5, 1.0, v5
	v_div_scale_f32 v6, s[18:19], v5, v5, v4
	v_rcp_f32_e32 v7, v6
	s_nop 0
	v_fma_f32 v14, -v6, v7, 1.0
	v_fmac_f32_e32 v7, v14, v7
	v_div_scale_f32 v14, vcc, v4, v5, v4
	v_mul_f32_e32 v15, v14, v7
	v_fma_f32 v43, -v6, v15, v14
	v_fmac_f32_e32 v15, v43, v7
	v_fma_f32 v6, -v6, v15, v14
	v_div_fmas_f32 v6, v6, v7, v15
	v_div_fixup_f32 v4, v6, v5, v4
	ds_write_b32 v26, v4 offset:17320
	ds_read_b32 v6, v36 offset:1040
	ds_read2_b32 v[4:5], v37 offset0:65 offset1:130
	s_waitcnt lgkmcnt(0)
	v_mul_f32_e32 v4, v1, v4
	v_fmac_f32_e32 v4, v0, v6
	v_fmac_f32_e32 v4, v2, v5
	v_add_f32_e32 v4, v3, v4
	v_mul_f32_e32 v5, 0xbfb8aa3b, v4
	v_exp_f32_e32 v5, v5
	s_nop 0
	v_add_f32_e32 v5, 1.0, v5
	v_div_scale_f32 v6, s[18:19], v5, v5, v4
	v_rcp_f32_e32 v7, v6
	s_nop 0
	v_fma_f32 v14, -v6, v7, 1.0
	v_fmac_f32_e32 v7, v14, v7
	v_div_scale_f32 v14, vcc, v4, v5, v4
	v_mul_f32_e32 v15, v14, v7
	v_fma_f32 v43, -v6, v15, v14
	v_fmac_f32_e32 v15, v43, v7
	v_fma_f32 v6, -v6, v15, v14
	v_div_fmas_f32 v6, v6, v7, v15
	v_div_fixup_f32 v4, v6, v5, v4
	ds_write_b32 v26, v4 offset:17336
	ds_read_b32 v6, v37 offset:1040
	ds_read2_b32 v[4:5], v38 offset0:65 offset1:130
	s_waitcnt lgkmcnt(0)
	v_mul_f32_e32 v4, v1, v4
	v_fmac_f32_e32 v4, v0, v6
	v_fmac_f32_e32 v4, v2, v5
	v_add_f32_e32 v4, v3, v4
	v_mul_f32_e32 v5, 0xbfb8aa3b, v4
	v_exp_f32_e32 v5, v5
	s_nop 0
	v_add_f32_e32 v5, 1.0, v5
	v_div_scale_f32 v6, s[18:19], v5, v5, v4
	v_rcp_f32_e32 v7, v6
	s_nop 0
	v_fma_f32 v14, -v6, v7, 1.0
	v_fmac_f32_e32 v7, v14, v7
	v_div_scale_f32 v14, vcc, v4, v5, v4
	v_mul_f32_e32 v15, v14, v7
	v_fma_f32 v43, -v6, v15, v14
	v_fmac_f32_e32 v15, v43, v7
	v_fma_f32 v6, -v6, v15, v14
	v_div_fmas_f32 v6, v6, v7, v15
	v_div_fixup_f32 v4, v6, v5, v4
	ds_write_b32 v26, v4 offset:17352
	ds_read_b32 v6, v38 offset:1040
	ds_read2_b32 v[4:5], v39 offset0:65 offset1:130
	s_waitcnt lgkmcnt(0)
	v_mul_f32_e32 v4, v1, v4
	v_fmac_f32_e32 v4, v0, v6
	v_fmac_f32_e32 v4, v2, v5
	v_add_f32_e32 v4, v3, v4
	v_mul_f32_e32 v5, 0xbfb8aa3b, v4
	v_exp_f32_e32 v5, v5
	s_nop 0
	v_add_f32_e32 v5, 1.0, v5
	v_div_scale_f32 v6, s[18:19], v5, v5, v4
	v_rcp_f32_e32 v7, v6
	s_nop 0
	v_fma_f32 v14, -v6, v7, 1.0
	v_fmac_f32_e32 v7, v14, v7
	v_div_scale_f32 v14, vcc, v4, v5, v4
	v_mul_f32_e32 v15, v14, v7
	v_fma_f32 v43, -v6, v15, v14
	v_fmac_f32_e32 v15, v43, v7
	v_fma_f32 v6, -v6, v15, v14
	v_div_fmas_f32 v6, v6, v7, v15
	v_div_fixup_f32 v4, v6, v5, v4
	ds_write_b32 v26, v4 offset:17368
	ds_read_b32 v6, v39 offset:1040
	ds_read2_b32 v[4:5], v40 offset0:65 offset1:130
	s_waitcnt lgkmcnt(0)
	v_mul_f32_e32 v4, v1, v4
	v_fmac_f32_e32 v4, v0, v6
	v_fmac_f32_e32 v4, v2, v5
	v_add_f32_e32 v4, v3, v4
	v_mul_f32_e32 v5, 0xbfb8aa3b, v4
	v_exp_f32_e32 v5, v5
	s_nop 0
	v_add_f32_e32 v5, 1.0, v5
	v_div_scale_f32 v6, s[18:19], v5, v5, v4
	v_rcp_f32_e32 v7, v6
	s_nop 0
	v_fma_f32 v14, -v6, v7, 1.0
	v_fmac_f32_e32 v7, v14, v7
	v_div_scale_f32 v14, vcc, v4, v5, v4
	v_mul_f32_e32 v15, v14, v7
	v_fma_f32 v43, -v6, v15, v14
	v_fmac_f32_e32 v15, v43, v7
	v_fma_f32 v6, -v6, v15, v14
	v_div_fmas_f32 v6, v6, v7, v15
	v_div_fixup_f32 v4, v6, v5, v4
	ds_write_b32 v26, v4 offset:17384
	ds_read_b32 v6, v40 offset:1040
	ds_read2_b32 v[4:5], v41 offset0:65 offset1:130
	s_waitcnt lgkmcnt(0)
	v_mul_f32_e32 v1, v1, v4
	v_fmac_f32_e32 v1, v0, v6
	v_fmac_f32_e32 v1, v2, v5
	v_add_f32_e32 v0, v3, v1
	v_mul_f32_e32 v1, 0xbfb8aa3b, v0
	v_exp_f32_e32 v1, v1
	s_nop 0
	v_add_f32_e32 v1, 1.0, v1
	v_div_scale_f32 v2, s[18:19], v1, v1, v0
	v_rcp_f32_e32 v3, v2
	s_nop 0
	v_fma_f32 v4, -v2, v3, 1.0
	v_fmac_f32_e32 v3, v4, v3
	v_div_scale_f32 v4, vcc, v0, v1, v0
	v_mul_f32_e32 v5, v4, v3
	v_fma_f32 v6, -v2, v5, v4
	v_fmac_f32_e32 v5, v6, v3
	v_fma_f32 v2, -v2, v5, v4
	v_div_fmas_f32 v2, v2, v3, v5
	v_div_fixup_f32 v0, v2, v1, v0
	ds_write_b32 v26, v0 offset:17400
	s_waitcnt lgkmcnt(0)
	s_barrier
	s_cbranch_scc0 .LBB0_416
	v_add_u32_e32 v0, 0x4200, v20
	ds_read2_b32 v[0:1], v0 offset0:66 offset1:131
	s_mov_b64 s[18:19], -1
	s_cmp_gt_u32 s15, 39
	s_waitcnt lgkmcnt(0)
	v_cvt_pk_bf16_f32 v0, v0, v1
	v_add_u32_e32 v1, 0x4400, v20
	ds_read2_b32 v[2:3], v1 offset0:68 offset1:133
	s_waitcnt lgkmcnt(0)
	v_cvt_pk_bf16_f32 v1, v2, v3
	v_add_u32_e32 v2, 0x4600, v20
	ds_read2_b32 v[2:3], v2 offset0:70 offset1:135
	s_waitcnt lgkmcnt(0)
	v_cvt_pk_bf16_f32 v2, v2, v3
	v_add_u32_e32 v3, 0x4800, v20
	ds_read2_b32 v[4:5], v3 offset0:72 offset1:137
	s_waitcnt lgkmcnt(0)
	v_cvt_pk_bf16_f32 v3, v4, v5
	v_add_u32_e32 v4, 0x4a00, v20
	ds_read2_b32 v[4:5], v4 offset0:74 offset1:139
	s_waitcnt lgkmcnt(0)
	v_cvt_pk_bf16_f32 v4, v4, v5
	v_add_u32_e32 v5, 0x4c00, v20
	ds_read2_b32 v[6:7], v5 offset0:76 offset1:141
	s_waitcnt lgkmcnt(0)
	v_cvt_pk_bf16_f32 v5, v6, v7
	v_add_u32_e32 v6, 0x4e00, v20
	ds_read2_b32 v[6:7], v6 offset0:78 offset1:143
	s_waitcnt lgkmcnt(0)
	v_cvt_pk_bf16_f32 v6, v6, v7
	v_add_u32_e32 v7, 0x5000, v20
	ds_read2_b32 v[14:15], v7 offset0:80 offset1:145
	s_waitcnt lgkmcnt(0)
	v_cvt_pk_bf16_f32 v7, v14, v15
	v_add_u32_e32 v14, s14, v19
	s_cbranch_scc0 .LBB0_414
	v_add_u32_e32 v15, s16, v21
	v_ashrrev_i32_e32 v44, 4, v14
	v_ashrrev_i32_e32 v45, 31, v44
	v_ashrrev_i32_e32 v46, 5, v15
	v_ashrrev_i32_e32 v47, 31, v46
	v_lshlrev_b64 v[44:45], 14, v[44:45]
	v_lshlrev_b64 v[46:47], 10, v[46:47]
	v_lshl_add_u64 v[44:45], v[10:11], 0, v[44:45]
	v_lshl_add_u64 v[44:45], v[44:45], 0, v[46:47]
	global_store_dwordx4 v[44:45], v[0:3], off
	global_store_dwordx4 v[44:45], v[4:7], off offset:256
	s_mov_b64 s[18:19], 0

; __global__ void __launch_bounds__(256, 2) hybrid_fwd(Params p) {
;     extern __shared__ __attribute__((aligned(16))) unsigned char lds[];
	.amdhsa_kernel _Z10hybrid_fwd6Params
		.amdhsa_group_segment_fixed_size 0
		.amdhsa_private_segment_fixed_size 0
		.amdhsa_kernarg_size 472
		.amdhsa_user_sgpr_count 2
		.amdhsa_user_sgpr_dispatch_ptr 0
		.amdhsa_user_sgpr_queue_ptr 0
		.amdhsa_user_sgpr_kernarg_segment_ptr 1
		.amdhsa_user_sgpr_dispatch_id 0
		.amdhsa_user_sgpr_kernarg_preload_length 0
		.amdhsa_user_sgpr_kernarg_preload_offset 0
		.amdhsa_user_sgpr_private_segment_size 0
		.amdhsa_uses_dynamic_stack 0
		.amdhsa_enable_private_segment 0
		.amdhsa_system_sgpr_workgroup_id_x 1
		.amdhsa_system_sgpr_workgroup_id_y 0
		.amdhsa_system_sgpr_workgroup_id_z 0
		.amdhsa_system_sgpr_workgroup_info 0
		.amdhsa_system_vgpr_workitem_id 2
		.amdhsa_next_free_vgpr 251
		.amdhsa_next_free_sgpr 102
		.amdhsa_accum_offset 252
		.amdhsa_reserve_vcc 1
		.amdhsa_float_round_mode_32 0
		.amdhsa_float_round_mode_16_64 0
		.amdhsa_float_denorm_mode_32 3
		.amdhsa_float_denorm_mode_16_64 3
		.amdhsa_dx10_clamp 1
		.amdhsa_ieee_mode 1
		.amdhsa_fp16_overflow 0
		.amdhsa_tg_split 0
		.amdhsa_exception_fp_ieee_invalid_op 0
		.amdhsa_exception_fp_denorm_src 0
		.amdhsa_exception_fp_ieee_div_zero 0
		.amdhsa_exception_fp_ieee_overflow 0
		.amdhsa_exception_fp_ieee_underflow 0
		.amdhsa_exception_fp_ieee_inexact 0
		.amdhsa_exception_int_div_zero 0
	.end_amdhsa_kernel

; __global__ void __launch_bounds__(256, 2) hybrid_fwd(Params p) {
amdhsa.kernels:
  - .agpr_count:     0
    .args:
      - .offset:         0
        .size:           216
        .value_kind:     by_value
      - .offset:         216
        .size:           4
        .value_kind:     hidden_block_count_x
      - .offset:         220
        .size:           4
        .value_kind:     hidden_block_count_y
      - .offset:         224
        .size:           4
        .value_kind:     hidden_block_count_z
      - .offset:         228
        .size:           2
        .value_kind:     hidden_group_size_x
      - .offset:         230
        .size:           2
        .value_kind:     hidden_group_size_y
      - .offset:         232
        .size:           2
        .value_kind:     hidden_group_size_z
      - .offset:         234
        .size:           2
        .value_kind:     hidden_remainder_x
      - .offset:         236
        .size:           2
        .value_kind:     hidden_remainder_y
      - .offset:         238
        .size:           2
        .value_kind:     hidden_remainder_z
      - .offset:         256
        .size:           8
        .value_kind:     hidden_global_offset_x
      - .offset:         264
        .size:           8
        .value_kind:     hidden_global_offset_y
      - .offset:         272
        .size:           8
        .value_kind:     hidden_global_offset_z
      - .offset:         280
        .size:           2
        .value_kind:     hidden_grid_dims
      - .offset:         304
        .size:           8
        .value_kind:     hidden_multigrid_sync_arg
      - .offset:         336
        .size:           4
        .value_kind:     hidden_dynamic_lds_size
    .group_segment_fixed_size: 0
    .kernarg_segment_align: 8
    .kernarg_segment_size: 472
    .language:       OpenCL C
    .language_version:
      - 2
      - 0
    .max_flat_workgroup_size: 256
    .name:           _Z10hybrid_fwd6Params
    .private_segment_fixed_size: 0
    .sgpr_count:     108
    .sgpr_spill_count: 155
    .symbol:         _Z10hybrid_fwd6Params.kd
    .uniform_work_group_size: 1
    .uses_dynamic_stack: false
    .vgpr_count:     251
    .vgpr_spill_count: 0
    .wavefront_size: 64
